# v15: prompt attention split between P3 and P4 moved from item 9000 to 6696 (same residue mod 128) to balance the two phases
# speedup vs baseline: 1.0069x; 1.0069x over previous
;     DI void init_s(f32x16& s, int) const { zero16(s); }
;     DI void init_s(f32x16& s, int) const { zero16(s); }
;     DI void init_s(f32x16& s, int) const { zero16(s); }
; #define REPS(k) for (int rep_ = 0, nrep_ = 1 + ((DUP_MASK >> (k)) & 1); rep_ < nrep_; ++rep_)
;     DI void init_s(f32x16& s, int tl) const { const int h = (threadIdx.x & 63) >> 5; const float c0 = slope2 * (float)(32 * tl) - lc;
; __global__ void __launch_bounds__(512, 2) fwd_kernel(Params P) {
;     ...
;     constexpr int ATT_SPLIT = 9000, ATT_TOTAL = 12288;
;     if (IN(3)) REPS(3) {
;         if (cu >= 16) for (int gt = (cu - 16) * 512 + tid; gt < 131072; gt += (G - 16) * 512) hgrn_scan(HST, HDV, P.out, gt, DRY);
;         if (cu < 16) { SchedUpS S{512, NPJ, 128 + (cu >> 2), cu & 3, (const char*)PROJ, (const char*)WT_UP}; EpiUp E{PROJ, DRY}; pg8::gemm_phase(lds, S, E); }
;         ATT_RUN(0, ATT_SPLIT, 1);
.LBB0_968:
	s_mulk_i32 s72, 0xf10
	s_add_i32 s78, s76, s72
	s_cmpk_gt_i32 s78, 0x1a27
	s_mov_b64 s[40:41], -1
	s_cbranch_scc1 .LBB0_959
	s_cmpk_gt_i32 s78, 0xfff
	v_lshlrev_b32_e32 v2, 1, v184
	s_cbranch_scc0 .LBB0_980
	s_add_i32 s40, s78, 0xfffff000
	s_lshr_b32 s88, s40, 10
	s_and_b32 s41, s78, 0x7f
	s_lshl_b32 s72, s88, 12
	s_lshl_b32 s40, s41, 5
	s_or_b32 s72, s72, s40
	v_or_b32_e32 v4, s72, v1
	s_bfe_u32 s85, s78, 0x30007
	v_mul_lo_u32 v4, v4, s59
	v_mov_b32_e32 v5, v3
	v_lshl_add_u64 v[4:5], v[4:5], 1, s[48:49]
	s_lshl_b32 s72, s85, 7
	s_load_dwordx2 s[86:87], s[0:1], 0x70
	v_lshl_add_u64 v[100:101], v[4:5], 0, s[72:73]
	s_lshl_b32 s72, s78, 10
	s_and_b32 s72, s72, 0x80000
	s_lshl_b32 s88, s88, 20
	s_or_b32 s72, s88, s72
	s_lshl_b32 s88, s85, 2
	v_mov_b32_e32 v4, s88
	v_lshl_add_u64 v[6:7], v[100:101], 0, v[2:3]
	s_waitcnt lgkmcnt(0)
	global_load_dword v9, v4, s[86:87]
	global_load_dwordx4 v[52:55], v[6:7], off
	global_load_dwordx4 v[56:59], v[6:7], off offset:32
	global_load_dwordx4 v[60:63], v[6:7], off offset:64
	global_load_dwordx4 v[64:67], v[6:7], off offset:96
	v_sub_u32_e64 v6, 4, s41 clamp
	v_add_u32_e32 v6, s41, v6
	v_add_u32_e32 v6, -4, v6
	v_ashrrev_i32_e32 v7, 31, v6
	v_lshl_add_u64 v[4:5], v[188:189], 0, s[72:73]
	v_lshlrev_b64 v[6:7], 12, v[6:7]
	v_lshl_add_u64 v[4:5], v[4:5], 0, v[6:7]
	global_load_dwordx4 v[80:83], v[4:5], off offset:3072
	global_load_dwordx4 v[76:79], v[4:5], off offset:2048
	global_load_dwordx4 v[72:75], v[4:5], off offset:1024
	global_load_dwordx4 v[68:71], v[4:5], off
	s_lshl_b32 s79, s79, 4
	s_lshl_b32 s86, s77, 4
	s_add_i32 s79, s79, s76
	s_sub_i32 s76, s79, s86
	s_mov_b32 s77, s73
	s_and_b32 s76, s76, 0x7f
	v_and_b32_e32 v11, 64, v185
	s_add_i32 s85, s85, 1
	v_cmp_lt_u64_e64 s[86:87], s[76:77], 4
	v_xor_b32_e32 v10, 32, v185
	v_add_u32_e32 v11, 64, v11
	v_cvt_f32_ubyte0_e32 v12, s85
	s_and_b64 s[86:87], s[86:87], exec
	v_or_b32_e32 v13, s40, v1
	v_cmp_lt_i32_e32 vcc, v10, v11
	v_exp_f32_e64 v11, -v12
	s_cselect_b32 s76, s76, 4
	s_min_u32 s87, s41, 4
	v_cvt_f32_u32_e32 v12, v13
	s_lshl_b32 s79, s76, 12
	s_sub_i32 s76, s41, s87
	s_ashr_i32 s77, s76, 31
	s_add_u32 s85, s79, 0xffffc000
	s_add_u32 s86, s79, 0x1000
	s_lshl_b64 s[76:77], s[76:77], 12
	v_cndmask_b32_e32 v10, v185, v10, vcc
	v_mul_f32_e32 v102, 0x3fb8aa3b, v11
	s_add_u32 s76, s76, s72
	v_mov_b32_e32 v18, v3
	v_mov_b32_e32 v19, v3
	v_mov_b32_e32 v4, v3
	v_mov_b32_e32 v5, v3
	v_mov_b32_e32 v6, v3
	v_mov_b32_e32 v7, v3
	v_mov_b32_e32 v8, v3
	v_lshlrev_b32_e32 v103, 2, v10
	v_mul_f32_e32 v124, v102, v12
	s_addc_u32 s77, s77, 0
	s_lshl_b32 s41, s87, 5
	v_mov_b32_e32 v10, v3
	v_mov_b32_e32 v11, v3
	v_mov_b32_e32 v12, v3
	v_mov_b32_e32 v13, v3
	v_mov_b32_e32 v14, v3
	v_mov_b32_e32 v15, v3
	v_mov_b32_e32 v16, v3
	v_mov_b32_e32 v17, v3
	v_pk_mul_f32 v[104:105], v[102:103], v[190:191] op_sel_hi:[0,1]
	v_pk_mul_f32 v[106:107], v[102:103], v[192:193] op_sel_hi:[0,1]
	v_pk_mul_f32 v[108:109], v[102:103], v[194:195] op_sel_hi:[0,1]
	v_pk_mul_f32 v[110:111], v[102:103], v[196:197] op_sel_hi:[0,1]
	v_pk_mul_f32 v[112:113], v[102:103], v[198:199] op_sel_hi:[0,1]
	v_pk_mul_f32 v[114:115], v[102:103], v[200:201] op_sel_hi:[0,1]
	v_pk_mul_f32 v[116:117], v[102:103], v[202:203] op_sel_hi:[0,1]
	v_pk_mul_f32 v[118:119], v[102:103], v[204:205] op_sel_hi:[0,1]
	v_lshl_add_u64 v[120:121], v[208:209], 0, s[76:77]
	s_sub_i32 s72, s40, s41
	v_lshl_add_u64 v[122:123], v[212:213], 0, s[76:77]
	v_mov_b32_e32 v125, 1.0
	s_mov_b64 s[40:41], 0
	s_waitcnt vmcnt(8)
	v_mul_f32_e32 v126, 0x3fb8aa3b, v9
	v_mov_b32_e32 v9, v3
	v_mov_b64_e32 v[34:35], v[18:19]
	v_mov_b64_e32 v[32:33], v[16:17]
	v_mov_b64_e32 v[30:31], v[14:15]
	v_mov_b64_e32 v[28:29], v[12:13]
	v_mov_b64_e32 v[26:27], v[10:11]
	v_mov_b64_e32 v[24:25], v[8:9]
	v_mov_b64_e32 v[22:23], v[6:7]
	v_mov_b64_e32 v[20:21], v[4:5]
	s_branch .LBB0_972

;     DI void init_s(f32x16& s, int) const { zero16(s); }
;     DI void init_s(f32x16& s, int) const { zero16(s); }
;     DI void init_s(f32x16& s, int) const { zero16(s); }
; #define REPS(k) for (int rep_ = 0, nrep_ = 1 + ((DUP_MASK >> (k)) & 1); rep_ < nrep_; ++rep_)
; #define SEAM(k) do { if (IN(k) && IN((k) + 1)) { if (P.ph_lo < 0) grid.sync(); else xcd_barrier(xbar); } } while (0)
;     DI void init_s(f32x16& s, int tl) const { const int h = (threadIdx.x & 63) >> 5; const float c0 = slope2 * (float)(32 * tl) - lc;
; __global__ void __launch_bounds__(512, 2) fwd_kernel(Params P) {
;     ...
;     constexpr int ATT_SPLIT = 9000, ATT_TOTAL = 12288;
;     if (IN(3)) REPS(3) {
;         if (cu >= 16) for (int gt = (cu - 16) * 512 + tid; gt < 131072; gt += (G - 16) * 512) hgrn_scan(HST, HDV, P.out, gt, DRY);
;         if (cu < 16) { SchedUpS S{512, NPJ, 128 + (cu >> 2), cu & 3, (const char*)PROJ, (const char*)WT_UP}; EpiUp E{PROJ, DRY}; pg8::gemm_phase(lds, S, E); }
;         ATT_RUN(0, ATT_SPLIT, 1);
;     }
;     SEAM(3);
;     if (IN(4)) REPS(4) {
;         if (cu < 16) { SchedOne S{1024, NPJ, 128 + (cu >> 2), cu & 3, (const char*)(PROJ + C_MIX), (const char*)WT_O}; EpiRes E{PROJ, XN, 1024}; pg8::gemm_phase(lds, S, E); }
;         ATT_RUN(ATT_SPLIT, ATT_TOTAL, 2);
.LBB0_1078:
	s_mul_i32 s40, s74, 0xf20
	s_add_i32 s76, s40, s68
	s_addk_i32 s76, 0x1a28
	s_cmpk_gt_i32 s76, 0x2fff
	s_mov_b64 s[40:41], -1
	s_cbranch_scc1 .LBB0_1069
	s_cmpk_gt_i32 s76, 0xfff
	v_lshlrev_b32_e32 v2, 1, v184
	s_cbranch_scc0 .LBB0_1090
	s_add_i32 s40, s76, 0xfffff000
	s_lshr_b32 s40, s40, 10
	s_and_b32 s84, s76, 0x7f
	s_lshl_b32 s41, s40, 12
	s_lshl_b32 s85, s84, 5
	s_or_b32 s41, s41, s85
	v_or_b32_e32 v4, s41, v185
	s_bfe_u32 s82, s76, 0x30007
	v_mul_lo_u32 v4, v4, s59
	v_mov_b32_e32 v5, v3
	v_lshl_add_u64 v[4:5], v[4:5], 1, s[48:49]
	s_lshl_b32 s74, s82, 7
	v_lshl_add_u64 v[100:101], v[4:5], 0, s[74:75]
	s_lshl_b32 s74, s82, 2
	v_mov_b32_e32 v4, s74
	v_lshl_add_u64 v[6:7], v[100:101], 0, v[2:3]
	global_load_dword v8, v4, s[72:73]
	global_load_dwordx4 v[52:55], v[6:7], off
	global_load_dwordx4 v[56:59], v[6:7], off offset:32
	global_load_dwordx4 v[60:63], v[6:7], off offset:64
	global_load_dwordx4 v[64:67], v[6:7], off offset:96
	v_sub_u32_e64 v6, 4, s84 clamp
	s_lshl_b32 s41, s76, 10
	v_add_u32_e32 v6, s84, v6
	s_and_b32 s41, s41, 0x80000
	s_lshl_b32 s40, s40, 20
	v_add_u32_e32 v6, -4, v6
	s_or_b32 s74, s40, s41
	v_ashrrev_i32_e32 v7, 31, v6
	v_lshl_add_u64 v[4:5], v[188:189], 0, s[74:75]
	v_lshlrev_b64 v[6:7], 12, v[6:7]
	v_lshl_add_u64 v[4:5], v[4:5], 0, v[6:7]
	global_load_dwordx4 v[80:83], v[4:5], off offset:3072
	global_load_dwordx4 v[76:79], v[4:5], off offset:2048
	global_load_dwordx4 v[72:75], v[4:5], off offset:1024
	global_load_dwordx4 v[68:71], v[4:5], off
	s_lshl_b32 s40, s77, 5
	s_lshl_b32 s69, s69, 5
	s_add_i32 s40, s40, s68
	s_sub_i32 s40, s40, s69
	s_add_i32 s40, s40, 40
	s_mov_b32 s41, s75
	s_and_b32 s40, s40, 0x7f
	v_and_b32_e32 v9, 64, v1
	s_add_i32 s82, s82, 1
	v_cmp_lt_u64_e64 s[68:69], s[40:41], 4
	v_xor_b32_e32 v7, 32, v1
	v_add_u32_e32 v9, 64, v9
	v_cvt_f32_ubyte0_e32 v10, s82
	s_and_b64 s[68:69], s[68:69], exec
	v_or_b32_e32 v11, s85, v185
	v_cmp_lt_i32_e32 vcc, v7, v9
	v_exp_f32_e64 v9, -v10
	s_cselect_b32 s40, s40, 4
	s_min_u32 s68, s84, 4
	v_cvt_f32_u32_e32 v10, v11
	s_lshl_b32 s77, s40, 12
	s_sub_i32 s40, s84, s68
	s_ashr_i32 s41, s40, 31
	s_add_u32 s82, s77, 0xffffc000
	s_add_u32 s84, s77, 0x1000
	s_lshl_b64 s[40:41], s[40:41], 12
	v_cndmask_b32_e32 v7, v1, v7, vcc
	v_mul_f32_e32 v102, 0x3fb8aa3b, v9
	s_add_u32 s40, s40, s74
	v_mov_b32_e32 v18, v3
	v_mov_b32_e32 v19, v3
	v_mov_b32_e32 v4, v3
	v_mov_b32_e32 v5, v3
	v_mov_b32_e32 v6, v3
	v_lshlrev_b32_e32 v103, 2, v7
	v_mul_f32_e32 v124, v102, v10
	s_addc_u32 s41, s41, 0
	s_lshl_b32 s68, s68, 5
	v_mov_b32_e32 v7, v3
	v_mov_b32_e32 v9, v3
	v_mov_b32_e32 v10, v3
	v_mov_b32_e32 v11, v3
	v_mov_b32_e32 v12, v3
	v_mov_b32_e32 v13, v3
	v_mov_b32_e32 v14, v3
	v_mov_b32_e32 v15, v3
	v_mov_b32_e32 v16, v3
	v_mov_b32_e32 v17, v3
	v_pk_mul_f32 v[104:105], v[102:103], v[190:191] op_sel_hi:[0,1]
	v_pk_mul_f32 v[106:107], v[102:103], v[192:193] op_sel_hi:[0,1]
	v_pk_mul_f32 v[108:109], v[102:103], v[194:195] op_sel_hi:[0,1]
	v_pk_mul_f32 v[110:111], v[102:103], v[196:197] op_sel_hi:[0,1]
	v_pk_mul_f32 v[112:113], v[102:103], v[198:199] op_sel_hi:[0,1]
	v_pk_mul_f32 v[114:115], v[102:103], v[200:201] op_sel_hi:[0,1]
	v_pk_mul_f32 v[116:117], v[102:103], v[202:203] op_sel_hi:[0,1]
	v_pk_mul_f32 v[118:119], v[102:103], v[204:205] op_sel_hi:[0,1]
	v_lshl_add_u64 v[120:121], v[208:209], 0, s[40:41]
	s_sub_i32 s74, s85, s68
	v_lshl_add_u64 v[122:123], v[212:213], 0, s[40:41]
	v_mov_b32_e32 v125, 1.0
	s_mov_b64 s[40:41], 0
	s_waitcnt vmcnt(8)
	v_mul_f32_e32 v126, 0x3fb8aa3b, v8
	v_mov_b32_e32 v8, v3
	v_mov_b64_e32 v[34:35], v[18:19]
	v_mov_b64_e32 v[32:33], v[16:17]
	v_mov_b64_e32 v[30:31], v[14:15]
	v_mov_b64_e32 v[28:29], v[12:13]
	v_mov_b64_e32 v[26:27], v[10:11]
	v_mov_b64_e32 v[24:25], v[8:9]
	v_mov_b64_e32 v[22:23], v[6:7]
	v_mov_b64_e32 v[20:21], v[4:5]
	s_branch .LBB0_1082
